# q up-projection epilogue row-statistic loads hoisted; memory cross-attention tile loads issued one tile ahead into spare registers
# baseline (speedup 1.0000x reference)
.LBB0_573:
	s_lshl_b32 s0, s83, 8
	v_mov_b32_e32 v134, v1
	v_mov_b32_e32 v140, v144
	s_add_i32 s0, s0, s71
	v_mov_b64_e32 v[138:139], s[28:29]
	v_add_u32_e32 v142, s0, v134
	v_ashrrev_i32_e32 v143, 31, v142
	v_lshl_add_u64 v[134:135], v[142:143], 2, s[42:43]
	global_load_dword v143, v[134:135], off
	global_load_dword v156, v[134:135], off offset:64
	global_load_dword v157, v[134:135], off offset:128
	global_load_dword v158, v[134:135], off offset:192
	global_load_dword v159, v[134:135], off offset:512
	global_load_dword v160, v[134:135], off offset:576
	global_load_dword v161, v[134:135], off offset:640
	global_load_dword v162, v[134:135], off offset:704
	s_lshl_b32 s0, s84, 8
	s_ashr_i32 s1, s0, 31
	v_lshlrev_b32_e32 v134, 2, v140
	s_lshl_b64 s[12:13], s[0:1], 1
	v_ashrrev_i32_e32 v135, 31, v134
	v_mad_i64_i32 v[140:141], s[0:1], v142, s82, v[138:139]
	v_lshl_add_u64 v[152:153], v[140:141], 0, s[12:13]
	v_lshlrev_b64 v[140:141], 1, v[134:135]
	v_add_u32_e32 v150, 16, v142
	v_ashrrev_i32_e32 v151, 31, v150
	s_waitcnt vmcnt(0)
	v_fmamk_f32 v134, v143, 0x3b2aaaab, v149
	v_mul_f32_e32 v135, 0x4b800000, v134
	v_cmp_gt_f32_e32 vcc, s81, v134
	s_nop 1
	v_cndmask_b32_e32 v134, v134, v135, vcc
	v_rsq_f32_e32 v143, v134
	v_lshl_add_u64 v[134:135], v[152:153], 0, s[8:9]
	v_lshl_add_u64 v[152:153], v[150:151], 2, s[42:43]
	v_lshl_add_u64 v[134:135], v[134:135], 0, v[140:141]
	v_mul_f32_e32 v151, 0x45800000, v143
	v_cndmask_b32_e32 v154, v143, v151, vcc
	v_pk_mul_f32 v[116:117], v[116:117], v[154:155] op_sel_hi:[1,0]
	v_pk_mul_f32 v[114:115], v[114:115], v[154:155] op_sel_hi:[1,0]
	v_pk_mul_f32 v[120:121], v[120:121], v[154:155] op_sel_hi:[1,0]
	v_pk_mul_f32 v[118:119], v[118:119], v[154:155] op_sel_hi:[1,0]
	v_pk_mul_f32 v[124:125], v[124:125], v[154:155] op_sel_hi:[1,0]
	v_pk_mul_f32 v[122:123], v[122:123], v[154:155] op_sel_hi:[1,0]
	v_pk_mul_f32 v[128:129], v[128:129], v[154:155] op_sel_hi:[1,0]
	v_pk_mul_f32 v[126:127], v[126:127], v[154:155] op_sel_hi:[1,0]
	v_cvt_pk_bf16_f32 v114, v114, v115
	v_cvt_pk_bf16_f32 v115, v116, v117
	v_cvt_pk_bf16_f32 v116, v118, v119
	v_cvt_pk_bf16_f32 v117, v120, v121
	v_cvt_pk_bf16_f32 v118, v122, v123
	v_cvt_pk_bf16_f32 v119, v124, v125
	v_cvt_pk_bf16_f32 v120, v126, v127
	v_cvt_pk_bf16_f32 v121, v128, v129
	global_store_dwordx2 v[134:135], v[114:115], off
	global_store_dwordx2 v[134:135], v[116:117], off offset:32
	global_store_dwordx2 v[134:135], v[118:119], off offset:256
	global_store_dwordx2 v[134:135], v[120:121], off offset:288
	v_add_u32_e32 v114, 32, v142
	v_ashrrev_i32_e32 v115, 31, v114
	v_mad_i64_i32 v[116:117], s[0:1], v150, s82, v[138:139]
	v_lshl_add_u64 v[116:117], v[116:117], 0, s[12:13]
	v_lshl_add_u64 v[116:117], v[116:117], 0, s[8:9]
	v_lshl_add_u64 v[116:117], v[116:117], 0, v[140:141]
	v_fmamk_f32 v118, v156, 0x3b2aaaab, v149
	v_mul_f32_e32 v119, 0x4b800000, v118
	v_cmp_gt_f32_e32 vcc, s81, v118
	s_nop 1
	v_cndmask_b32_e32 v118, v118, v119, vcc
	v_rsq_f32_e32 v120, v118
	v_lshl_add_u64 v[118:119], v[114:115], 2, s[42:43]
	v_mul_f32_e32 v115, 0x45800000, v120
	v_cndmask_b32_e32 v120, v120, v115, vcc
	v_pk_mul_f32 v[100:101], v[100:101], v[120:121] op_sel_hi:[1,0]
	v_pk_mul_f32 v[98:99], v[98:99], v[120:121] op_sel_hi:[1,0]
	v_pk_mul_f32 v[104:105], v[104:105], v[120:121] op_sel_hi:[1,0]
	v_pk_mul_f32 v[102:103], v[102:103], v[120:121] op_sel_hi:[1,0]
	v_pk_mul_f32 v[108:109], v[108:109], v[120:121] op_sel_hi:[1,0]
	v_pk_mul_f32 v[106:107], v[106:107], v[120:121] op_sel_hi:[1,0]
	v_pk_mul_f32 v[112:113], v[112:113], v[120:121] op_sel_hi:[1,0]
	v_pk_mul_f32 v[110:111], v[110:111], v[120:121] op_sel_hi:[1,0]
	v_cvt_pk_bf16_f32 v98, v98, v99
	v_cvt_pk_bf16_f32 v99, v100, v101
	v_cvt_pk_bf16_f32 v100, v102, v103
	v_cvt_pk_bf16_f32 v101, v104, v105
	v_cvt_pk_bf16_f32 v102, v106, v107
	v_cvt_pk_bf16_f32 v103, v108, v109
	v_cvt_pk_bf16_f32 v104, v110, v111
	v_cvt_pk_bf16_f32 v105, v112, v113
	global_store_dwordx2 v[116:117], v[98:99], off
	global_store_dwordx2 v[116:117], v[100:101], off offset:32
	global_store_dwordx2 v[116:117], v[102:103], off offset:256
	global_store_dwordx2 v[116:117], v[104:105], off offset:288
	v_add_u32_e32 v98, 48, v142
	v_ashrrev_i32_e32 v99, 31, v98
	v_mad_i64_i32 v[100:101], s[0:1], v114, s82, v[138:139]
	v_lshl_add_u64 v[100:101], v[100:101], 0, s[12:13]
	v_lshl_add_u64 v[100:101], v[100:101], 0, s[8:9]
	v_lshl_add_u64 v[100:101], v[100:101], 0, v[140:141]
	v_fmamk_f32 v102, v157, 0x3b2aaaab, v149
	v_mul_f32_e32 v103, 0x4b800000, v102
	v_cmp_gt_f32_e32 vcc, s81, v102
	s_nop 1
	v_cndmask_b32_e32 v102, v102, v103, vcc
	v_rsq_f32_e32 v104, v102
	v_lshl_add_u64 v[102:103], v[98:99], 2, s[42:43]
	v_mul_f32_e32 v99, 0x45800000, v104
	v_cndmask_b32_e32 v104, v104, v99, vcc
	v_pk_mul_f32 v[84:85], v[84:85], v[104:105] op_sel_hi:[1,0]
	v_pk_mul_f32 v[82:83], v[82:83], v[104:105] op_sel_hi:[1,0]
	v_pk_mul_f32 v[88:89], v[88:89], v[104:105] op_sel_hi:[1,0]
	v_pk_mul_f32 v[86:87], v[86:87], v[104:105] op_sel_hi:[1,0]
	v_pk_mul_f32 v[92:93], v[92:93], v[104:105] op_sel_hi:[1,0]
	v_pk_mul_f32 v[90:91], v[90:91], v[104:105] op_sel_hi:[1,0]
	v_pk_mul_f32 v[96:97], v[96:97], v[104:105] op_sel_hi:[1,0]
	v_pk_mul_f32 v[94:95], v[94:95], v[104:105] op_sel_hi:[1,0]
	v_cvt_pk_bf16_f32 v82, v82, v83
	v_cvt_pk_bf16_f32 v83, v84, v85
	v_cvt_pk_bf16_f32 v84, v86, v87
	v_cvt_pk_bf16_f32 v85, v88, v89
	v_cvt_pk_bf16_f32 v86, v90, v91
	v_cvt_pk_bf16_f32 v87, v92, v93
	v_cvt_pk_bf16_f32 v88, v94, v95
	v_cvt_pk_bf16_f32 v89, v96, v97
	global_store_dwordx2 v[100:101], v[82:83], off
	global_store_dwordx2 v[100:101], v[84:85], off offset:32
	global_store_dwordx2 v[100:101], v[86:87], off offset:256
	global_store_dwordx2 v[100:101], v[88:89], off offset:288
	v_add_u32_e32 v82, 0x80, v142
	v_ashrrev_i32_e32 v83, 31, v82
	v_mad_i64_i32 v[84:85], s[0:1], v98, s82, v[138:139]
	v_lshl_add_u64 v[84:85], v[84:85], 0, s[12:13]
	v_lshl_add_u64 v[84:85], v[84:85], 0, s[8:9]
	v_lshl_add_u64 v[84:85], v[84:85], 0, v[140:141]
	v_fmamk_f32 v86, v158, 0x3b2aaaab, v149
	v_mul_f32_e32 v87, 0x4b800000, v86
	v_cmp_gt_f32_e32 vcc, s81, v86
	s_nop 1
	v_cndmask_b32_e32 v86, v86, v87, vcc
	v_rsq_f32_e32 v88, v86
	v_lshl_add_u64 v[86:87], v[82:83], 2, s[42:43]
	v_mul_f32_e32 v83, 0x45800000, v88
	v_cndmask_b32_e32 v88, v88, v83, vcc
	v_pk_mul_f32 v[68:69], v[68:69], v[88:89] op_sel_hi:[1,0]
	v_pk_mul_f32 v[66:67], v[66:67], v[88:89] op_sel_hi:[1,0]
	v_pk_mul_f32 v[72:73], v[72:73], v[88:89] op_sel_hi:[1,0]
	v_pk_mul_f32 v[70:71], v[70:71], v[88:89] op_sel_hi:[1,0]
	v_pk_mul_f32 v[76:77], v[76:77], v[88:89] op_sel_hi:[1,0]
	v_pk_mul_f32 v[74:75], v[74:75], v[88:89] op_sel_hi:[1,0]
	v_pk_mul_f32 v[80:81], v[80:81], v[88:89] op_sel_hi:[1,0]
	v_pk_mul_f32 v[78:79], v[78:79], v[88:89] op_sel_hi:[1,0]
	v_cvt_pk_bf16_f32 v66, v66, v67
	v_cvt_pk_bf16_f32 v67, v68, v69
	v_cvt_pk_bf16_f32 v68, v70, v71
	v_cvt_pk_bf16_f32 v69, v72, v73
	v_cvt_pk_bf16_f32 v70, v74, v75
	v_cvt_pk_bf16_f32 v71, v76, v77
	v_cvt_pk_bf16_f32 v72, v78, v79
	v_cvt_pk_bf16_f32 v73, v80, v81
	global_store_dwordx2 v[84:85], v[66:67], off
	global_store_dwordx2 v[84:85], v[68:69], off offset:32
	global_store_dwordx2 v[84:85], v[70:71], off offset:256
	global_store_dwordx2 v[84:85], v[72:73], off offset:288
	v_add_u32_e32 v66, 0x90, v142
	v_ashrrev_i32_e32 v67, 31, v66
	v_mad_i64_i32 v[68:69], s[0:1], v82, s82, v[138:139]
	v_lshl_add_u64 v[68:69], v[68:69], 0, s[12:13]
	v_lshl_add_u64 v[68:69], v[68:69], 0, s[8:9]
	v_lshl_add_u64 v[68:69], v[68:69], 0, v[140:141]
	v_fmamk_f32 v70, v159, 0x3b2aaaab, v149
	v_mul_f32_e32 v71, 0x4b800000, v70
	v_cmp_gt_f32_e32 vcc, s81, v70
	s_nop 1
	v_cndmask_b32_e32 v70, v70, v71, vcc
	v_rsq_f32_e32 v72, v70
	v_lshl_add_u64 v[70:71], v[66:67], 2, s[42:43]
	v_mul_f32_e32 v67, 0x45800000, v72
	v_cndmask_b32_e32 v72, v72, v67, vcc
	v_pk_mul_f32 v[52:53], v[52:53], v[72:73] op_sel_hi:[1,0]
	v_pk_mul_f32 v[50:51], v[50:51], v[72:73] op_sel_hi:[1,0]
	v_pk_mul_f32 v[56:57], v[56:57], v[72:73] op_sel_hi:[1,0]
	v_pk_mul_f32 v[54:55], v[54:55], v[72:73] op_sel_hi:[1,0]
	v_pk_mul_f32 v[60:61], v[60:61], v[72:73] op_sel_hi:[1,0]
	v_pk_mul_f32 v[58:59], v[58:59], v[72:73] op_sel_hi:[1,0]
	v_pk_mul_f32 v[64:65], v[64:65], v[72:73] op_sel_hi:[1,0]
	v_pk_mul_f32 v[62:63], v[62:63], v[72:73] op_sel_hi:[1,0]
	v_cvt_pk_bf16_f32 v50, v50, v51
	v_cvt_pk_bf16_f32 v51, v52, v53
	v_cvt_pk_bf16_f32 v52, v54, v55
	v_cvt_pk_bf16_f32 v53, v56, v57
	v_cvt_pk_bf16_f32 v54, v58, v59
	v_cvt_pk_bf16_f32 v55, v60, v61
	v_cvt_pk_bf16_f32 v56, v62, v63
	v_cvt_pk_bf16_f32 v57, v64, v65
	global_store_dwordx2 v[68:69], v[50:51], off
	global_store_dwordx2 v[68:69], v[52:53], off offset:32
	global_store_dwordx2 v[68:69], v[54:55], off offset:256
	global_store_dwordx2 v[68:69], v[56:57], off offset:288
	v_add_u32_e32 v50, 0xa0, v142
	v_ashrrev_i32_e32 v51, 31, v50
	v_mad_i64_i32 v[52:53], s[0:1], v66, s82, v[138:139]
	v_lshl_add_u64 v[52:53], v[52:53], 0, s[12:13]
	v_lshl_add_u64 v[52:53], v[52:53], 0, s[8:9]
	v_lshl_add_u64 v[52:53], v[52:53], 0, v[140:141]
	v_fmamk_f32 v54, v160, 0x3b2aaaab, v149
	v_mul_f32_e32 v55, 0x4b800000, v54
	v_cmp_gt_f32_e32 vcc, s81, v54
	s_nop 1
	v_cndmask_b32_e32 v54, v54, v55, vcc
	v_rsq_f32_e32 v56, v54
	v_lshl_add_u64 v[54:55], v[50:51], 2, s[42:43]
	v_mul_f32_e32 v51, 0x45800000, v56
	v_cndmask_b32_e32 v56, v56, v51, vcc
	v_pk_mul_f32 v[36:37], v[36:37], v[56:57] op_sel_hi:[1,0]
	v_pk_mul_f32 v[34:35], v[34:35], v[56:57] op_sel_hi:[1,0]
	v_pk_mul_f32 v[40:41], v[40:41], v[56:57] op_sel_hi:[1,0]
	v_pk_mul_f32 v[38:39], v[38:39], v[56:57] op_sel_hi:[1,0]
	v_pk_mul_f32 v[44:45], v[44:45], v[56:57] op_sel_hi:[1,0]
	v_pk_mul_f32 v[42:43], v[42:43], v[56:57] op_sel_hi:[1,0]
	v_pk_mul_f32 v[48:49], v[48:49], v[56:57] op_sel_hi:[1,0]
	v_pk_mul_f32 v[46:47], v[46:47], v[56:57] op_sel_hi:[1,0]
	v_cvt_pk_bf16_f32 v34, v34, v35
	v_cvt_pk_bf16_f32 v35, v36, v37
	v_cvt_pk_bf16_f32 v36, v38, v39
	v_cvt_pk_bf16_f32 v37, v40, v41
	v_cvt_pk_bf16_f32 v38, v42, v43
	v_cvt_pk_bf16_f32 v39, v44, v45
	v_cvt_pk_bf16_f32 v40, v46, v47
	v_cvt_pk_bf16_f32 v41, v48, v49
	global_store_dwordx2 v[52:53], v[34:35], off
	global_store_dwordx2 v[52:53], v[36:37], off offset:32
	global_store_dwordx2 v[52:53], v[38:39], off offset:256
	global_store_dwordx2 v[52:53], v[40:41], off offset:288
	v_add_u32_e32 v34, 0xb0, v142
	v_ashrrev_i32_e32 v35, 31, v34
	v_mad_i64_i32 v[36:37], s[0:1], v50, s82, v[138:139]
	v_lshl_add_u64 v[36:37], v[36:37], 0, s[12:13]
	v_lshl_add_u64 v[36:37], v[36:37], 0, s[8:9]
	v_lshl_add_u64 v[36:37], v[36:37], 0, v[140:141]
	v_fmamk_f32 v38, v161, 0x3b2aaaab, v149
	v_mul_f32_e32 v39, 0x4b800000, v38
	v_cmp_gt_f32_e32 vcc, s81, v38
	s_nop 1
	v_cndmask_b32_e32 v38, v38, v39, vcc
	v_rsq_f32_e32 v40, v38
	v_lshl_add_u64 v[38:39], v[34:35], 2, s[42:43]
	v_mul_f32_e32 v35, 0x45800000, v40
	v_cndmask_b32_e32 v40, v40, v35, vcc
	v_pk_mul_f32 v[20:21], v[20:21], v[40:41] op_sel_hi:[1,0]
	v_pk_mul_f32 v[18:19], v[18:19], v[40:41] op_sel_hi:[1,0]
	v_pk_mul_f32 v[24:25], v[24:25], v[40:41] op_sel_hi:[1,0]
	v_pk_mul_f32 v[22:23], v[22:23], v[40:41] op_sel_hi:[1,0]
	v_pk_mul_f32 v[28:29], v[28:29], v[40:41] op_sel_hi:[1,0]
	v_pk_mul_f32 v[26:27], v[26:27], v[40:41] op_sel_hi:[1,0]
	v_pk_mul_f32 v[32:33], v[32:33], v[40:41] op_sel_hi:[1,0]
	v_pk_mul_f32 v[30:31], v[30:31], v[40:41] op_sel_hi:[1,0]
	v_cvt_pk_bf16_f32 v18, v18, v19
	v_cvt_pk_bf16_f32 v19, v20, v21
	v_cvt_pk_bf16_f32 v20, v22, v23
	v_cvt_pk_bf16_f32 v21, v24, v25
	v_cvt_pk_bf16_f32 v22, v26, v27
	v_cvt_pk_bf16_f32 v23, v28, v29
	v_cvt_pk_bf16_f32 v24, v30, v31
	v_cvt_pk_bf16_f32 v25, v32, v33
	global_store_dwordx2 v[36:37], v[18:19], off
	global_store_dwordx2 v[36:37], v[20:21], off offset:32
	global_store_dwordx2 v[36:37], v[22:23], off offset:256
	global_store_dwordx2 v[36:37], v[24:25], off offset:288
	v_mad_i64_i32 v[18:19], s[0:1], v34, s82, v[138:139]
	v_lshl_add_u64 v[18:19], v[18:19], 0, s[12:13]
	v_lshl_add_u64 v[18:19], v[18:19], 0, s[8:9]
	s_and_b64 vcc, exec, s[6:7]
	v_lshl_add_u64 v[18:19], v[18:19], 0, v[140:141]
	v_fmamk_f32 v20, v162, 0x3b2aaaab, v149
	v_mul_f32_e32 v21, 0x4b800000, v20
	v_cmp_gt_f32_e64 s[0:1], s81, v20
	s_nop 1
	v_cndmask_b32_e64 v20, v20, v21, s[0:1]
	v_rsq_f32_e32 v20, v20
	s_nop 0
	v_mul_f32_e32 v21, 0x45800000, v20
	v_cndmask_b32_e64 v20, v20, v21, s[0:1]
	v_pk_mul_f32 v[4:5], v[4:5], v[20:21] op_sel_hi:[1,0]
	v_pk_mul_f32 v[2:3], v[2:3], v[20:21] op_sel_hi:[1,0]
	v_pk_mul_f32 v[8:9], v[8:9], v[20:21] op_sel_hi:[1,0]
	v_pk_mul_f32 v[6:7], v[6:7], v[20:21] op_sel_hi:[1,0]
	v_pk_mul_f32 v[12:13], v[12:13], v[20:21] op_sel_hi:[1,0]
	v_pk_mul_f32 v[10:11], v[10:11], v[20:21] op_sel_hi:[1,0]
	v_pk_mul_f32 v[16:17], v[16:17], v[20:21] op_sel_hi:[1,0]
	v_pk_mul_f32 v[14:15], v[14:15], v[20:21] op_sel_hi:[1,0]
	v_cvt_pk_bf16_f32 v2, v2, v3
	v_cvt_pk_bf16_f32 v3, v4, v5
	s_mov_b64 s[0:1], -1
	v_cvt_pk_bf16_f32 v4, v6, v7
	v_cvt_pk_bf16_f32 v5, v8, v9
	v_cvt_pk_bf16_f32 v6, v10, v11
	v_cvt_pk_bf16_f32 v7, v12, v13
	v_cvt_pk_bf16_f32 v8, v14, v15
	v_cvt_pk_bf16_f32 v9, v16, v17
	global_store_dwordx2 v[18:19], v[2:3], off
	global_store_dwordx2 v[18:19], v[4:5], off offset:32
	global_store_dwordx2 v[18:19], v[6:7], off offset:256
	global_store_dwordx2 v[18:19], v[8:9], off offset:288
	s_cbranch_vccnz .LBB0_564
	s_andn2_b64 vcc, exec, s[10:11]
	s_cbranch_vccnz .LBB0_563
	s_barrier
	s_branch .LBB0_563

.LBB0_830:
	s_lshl_b32 s9, s12, 5
	s_and_b32 s8, s9, 0xffffff80
	s_addk_i32 s9, 0xc000
	s_and_b32 s42, s14, 3
	s_lshr_b32 s9, s9, 12
	s_lshl_b32 s41, s42, 8
	s_and_b32 s11, s12, 3
	s_ashr_i32 s10, s12, 8
	s_add_i32 s9, s9, 2
	s_cmpk_lt_i32 s8, 0x4000
	s_cselect_b32 s10, s10, s9
	s_ashr_i32 s9, s8, 31
	s_lshl_b64 s[8:9], s[8:9], 10
	v_mov_b32_e32 v50, v1
	s_add_u32 s8, s30, s8
	s_addc_u32 s9, s31, s9
	v_ashrrev_i32_e32 v2, 1, v50
	s_lshl_b32 s11, s11, 8
	v_bfi_b32 v2, s15, v2, v50
	s_add_u32 s8, s8, s11
	v_ashrrev_i32_e32 v3, 31, v2
	s_addc_u32 s9, s9, 0
	v_bfe_u32 v51, v50, 5, 1
	v_lshlrev_b64 v[2:3], 10, v[2:3]
	v_lshl_add_u64 v[136:137], s[8:9], 0, v[2:3]
	v_lshlrev_b32_e32 v134, 4, v51
	v_lshl_add_u64 v[18:19], v[136:137], 0, v[134:135]
	s_barrier
	global_load_dwordx4 v[26:29], v[18:19], off offset:224
	global_load_dwordx4 v[34:37], v[18:19], off offset:192
	global_load_dwordx4 v[42:45], v[18:19], off offset:160
	global_load_dwordx4 v[52:55], v[18:19], off offset:128
	v_cmp_lt_i32_e32 vcc, v158, v159
	v_readlane_b32 s44, v255, 18
	v_lshlrev_b32_e32 v144, 5, v51
	v_cndmask_b32_e32 v2, v157, v158, vcc
	v_readlane_b32 s54, v255, 28
	v_readlane_b32 s55, v255, 29
	v_lshlrev_b32_e32 v139, 2, v2
	s_nop 3
	global_load_dwordx4 v[2:5], v144, s[54:55] offset:336
	global_load_dwordx4 v[6:9], v144, s[54:55] offset:320
	global_load_dwordx4 v[10:13], v144, s[54:55] offset:272
	global_load_dwordx4 v[14:17], v144, s[54:55] offset:256
	global_load_dwordx4 v[56:59], v[18:19], off
	global_load_dwordx4 v[60:63], v[18:19], off offset:32
	global_load_dwordx4 v[64:67], v[18:19], off offset:64
	global_load_dwordx4 v[68:71], v[18:19], off offset:96
	v_lshlrev_b32_e32 v138, 3, v51
	s_ashr_i32 s11, s10, 31
	s_lshl_b64 s[8:9], s[10:11], 18
	s_lshl_b32 s10, s10, 2
	s_or_b32 s10, s10, s42
	s_ashr_i32 s11, s10, 31
	s_lshl_b64 s[10:11], s[10:11], 16
	s_add_u32 s8, s8, 0x2250000
	s_addc_u32 s9, s9, 0
	v_mov_b32_e32 v175, 0xff800000
	v_mov_b32_e32 v178, 0
	v_readlane_b32 s45, v255, 19
	v_readlane_b32 s46, v255, 20
	v_readlane_b32 s47, v255, 21
	v_readlane_b32 s48, v255, 22
	v_readlane_b32 s49, v255, 23
	v_readlane_b32 s50, v255, 24
	v_readlane_b32 s51, v255, 25
	v_readlane_b32 s52, v255, 26
	v_readlane_b32 s53, v255, 27
	v_readlane_b32 s56, v255, 30
	v_readlane_b32 s57, v255, 31
	v_readlane_b32 s58, v255, 32
	v_readlane_b32 s59, v255, 33
	s_waitcnt vmcnt(11)
	v_and_b32_e32 v25, 0xffff0000, v26
	s_waitcnt vmcnt(10)
	v_and_b32_e32 v33, 0xffff0000, v34
	v_lshlrev_b32_e32 v24, 16, v26
	v_lshlrev_b32_e32 v32, 16, v34
	v_mov_b32_e32 v82, v33
	v_mov_b32_e32 v83, v25
	v_lshlrev_b32_e32 v22, 16, v27
	v_lshlrev_b32_e32 v30, 16, v35
	v_mov_b32_e32 v80, v32
	v_mov_b32_e32 v81, v24
	v_pk_mul_f32 v[82:83], v[82:83], v[82:83]
	v_and_b32_e32 v23, 0xffff0000, v27
	v_and_b32_e32 v31, 0xffff0000, v35
	v_mov_b32_e32 v76, v30
	v_mov_b32_e32 v77, v22
	v_pk_fma_f32 v[80:81], v[80:81], v[80:81], v[82:83]
	v_lshlrev_b32_e32 v20, 16, v28
	v_and_b32_e32 v21, 0xffff0000, v28
	v_lshlrev_b32_e32 v28, 16, v36
	v_mov_b32_e32 v78, v31
	v_mov_b32_e32 v79, v23
	v_pk_fma_f32 v[76:77], v[76:77], v[76:77], v[80:81]
	v_lshlrev_b32_e32 v18, 16, v29
	v_and_b32_e32 v19, 0xffff0000, v29
	v_and_b32_e32 v29, 0xffff0000, v36
	v_mov_b32_e32 v72, v28
	v_mov_b32_e32 v73, v20
	v_pk_fma_f32 v[76:77], v[78:79], v[78:79], v[76:77]
	v_lshlrev_b32_e32 v26, 16, v37
	v_mov_b32_e32 v74, v29
	v_mov_b32_e32 v75, v21
	v_pk_fma_f32 v[72:73], v[72:73], v[72:73], v[76:77]
	v_and_b32_e32 v27, 0xffff0000, v37
	v_mov_b32_e32 v48, v26
	v_mov_b32_e32 v49, v18
	v_pk_fma_f32 v[72:73], v[74:75], v[74:75], v[72:73]
	s_waitcnt vmcnt(9)
	v_lshlrev_b32_e32 v34, 16, v45
	v_and_b32_e32 v35, 0xffff0000, v45
	v_lshlrev_b32_e32 v36, 16, v44
	v_and_b32_e32 v37, 0xffff0000, v44
	v_lshlrev_b32_e32 v38, 16, v43
	v_and_b32_e32 v39, 0xffff0000, v43
	v_lshlrev_b32_e32 v40, 16, v42
	v_and_b32_e32 v41, 0xffff0000, v42
	s_waitcnt vmcnt(8)
	v_lshlrev_b32_e32 v42, 16, v55
	v_and_b32_e32 v43, 0xffff0000, v55
	v_lshlrev_b32_e32 v44, 16, v54
	v_and_b32_e32 v45, 0xffff0000, v54
	v_mov_b32_e32 v54, v27
	v_mov_b32_e32 v55, v19
	v_pk_fma_f32 v[48:49], v[48:49], v[48:49], v[72:73]
	v_mov_b32_e32 v83, v41
	v_pk_fma_f32 v[92:93], v[54:55], v[54:55], v[48:49]
	v_and_b32_e32 v49, 0xffff0000, v52
	v_lshlrev_b32_e32 v48, 16, v52
	v_mov_b32_e32 v82, v49
	v_lshlrev_b32_e32 v46, 16, v53
	v_mov_b32_e32 v80, v48
	v_mov_b32_e32 v81, v40
	v_pk_mul_f32 v[82:83], v[82:83], v[82:83]
	v_and_b32_e32 v47, 0xffff0000, v53
	v_mov_b32_e32 v76, v46
	v_mov_b32_e32 v77, v38
	v_pk_fma_f32 v[80:81], v[80:81], v[80:81], v[82:83]
	v_mov_b32_e32 v78, v47
	v_mov_b32_e32 v79, v39
	v_pk_fma_f32 v[76:77], v[76:77], v[76:77], v[80:81]
	v_mov_b32_e32 v72, v44
	v_mov_b32_e32 v73, v36
	v_pk_fma_f32 v[76:77], v[78:79], v[78:79], v[76:77]
	v_mov_b32_e32 v74, v45
	v_mov_b32_e32 v75, v37
	v_pk_fma_f32 v[72:73], v[72:73], v[72:73], v[76:77]
	v_mov_b32_e32 v52, v42
	v_mov_b32_e32 v53, v34
	v_pk_fma_f32 v[72:73], v[74:75], v[74:75], v[72:73]
	v_mov_b32_e32 v54, v43
	v_mov_b32_e32 v55, v35
	v_pk_fma_f32 v[52:53], v[52:53], v[52:53], v[72:73]
	s_waitcnt vmcnt(0)
	v_lshlrev_b32_e32 v96, 16, v71
	v_pk_fma_f32 v[94:95], v[54:55], v[54:55], v[52:53]
	v_and_b32_e32 v97, 0xffff0000, v71
	global_load_dwordx4 v[52:55], v144, s[54:55] offset:208
	global_load_dwordx4 v[72:75], v144, s[54:55] offset:192
	v_lshlrev_b32_e32 v112, 16, v70
	v_and_b32_e32 v113, 0xffff0000, v70
	v_lshlrev_b32_e32 v114, 16, v69
	v_and_b32_e32 v115, 0xffff0000, v69
	v_lshlrev_b32_e32 v110, 16, v68
	v_and_b32_e32 v111, 0xffff0000, v68
	v_lshlrev_b32_e32 v116, 16, v67
	v_and_b32_e32 v117, 0xffff0000, v67
	global_load_dwordx4 v[68:71], v144, s[54:55] offset:144
	global_load_dwordx4 v[76:79], v144, s[54:55] offset:128
	v_lshlrev_b32_e32 v108, 16, v66
	v_and_b32_e32 v109, 0xffff0000, v66
	v_lshlrev_b32_e32 v118, 16, v65
	v_and_b32_e32 v119, 0xffff0000, v65
	v_lshlrev_b32_e32 v106, 16, v64
	v_and_b32_e32 v107, 0xffff0000, v64
	global_load_dwordx4 v[64:67], v144, s[54:55] offset:16
	global_load_dwordx4 v[80:83], v144, s[54:55]
	v_mov_b32_e32 v104, v107
	v_mov_b32_e32 v105, v111
	v_mov_b32_e32 v102, v106
	v_mov_b32_e32 v103, v110
	v_pk_mul_f32 v[104:105], v[104:105], v[104:105]
	v_mov_b32_e32 v88, v118
	v_mov_b32_e32 v89, v114
	v_pk_fma_f32 v[102:103], v[102:103], v[102:103], v[104:105]
	v_mov_b32_e32 v90, v119
	v_mov_b32_e32 v91, v115
	v_pk_fma_f32 v[88:89], v[88:89], v[88:89], v[102:103]
	v_mov_b32_e32 v84, v108
	v_mov_b32_e32 v85, v112
	v_pk_fma_f32 v[88:89], v[90:91], v[90:91], v[88:89]
	v_mov_b32_e32 v86, v109
	v_mov_b32_e32 v87, v113
	v_pk_fma_f32 v[84:85], v[84:85], v[84:85], v[88:89]
	v_mov_b32_e32 v98, v116
	v_pk_fma_f32 v[102:103], v[86:87], v[86:87], v[84:85]
	global_load_dwordx4 v[84:87], v144, s[54:55] offset:80
	global_load_dwordx4 v[88:91], v144, s[54:55] offset:64
	v_mov_b32_e32 v99, v96
	v_pk_fma_f32 v[98:99], v[98:99], v[98:99], v[102:103]
	v_and_b32_e32 v103, 0xffff0000, v60
	v_and_b32_e32 v133, 0xffff0000, v56
	v_lshlrev_b32_e32 v102, 16, v60
	v_lshlrev_b32_e32 v132, 16, v56
	v_mov_b32_e32 v142, v133
	v_mov_b32_e32 v143, v103
	v_lshlrev_b32_e32 v122, 16, v61
	v_lshlrev_b32_e32 v130, 16, v57
	v_mov_b32_e32 v140, v132
	v_mov_b32_e32 v141, v102
	v_pk_mul_f32 v[142:143], v[142:143], v[142:143]
	v_mov_b32_e32 v100, v117
	v_mov_b32_e32 v101, v97
	v_and_b32_e32 v123, 0xffff0000, v61
	v_and_b32_e32 v131, 0xffff0000, v57
	v_mov_b32_e32 v126, v130
	v_mov_b32_e32 v127, v122
	v_pk_fma_f32 v[140:141], v[140:141], v[140:141], v[142:143]
	v_pk_fma_f32 v[98:99], v[100:101], v[100:101], v[98:99]
	v_lshlrev_b32_e32 v104, 16, v62
	v_lshlrev_b32_e32 v100, 16, v58
	v_mov_b32_e32 v128, v131
	v_mov_b32_e32 v129, v123
	v_pk_fma_f32 v[126:127], v[126:127], v[126:127], v[140:141]
	v_and_b32_e32 v105, 0xffff0000, v62
	v_and_b32_e32 v101, 0xffff0000, v58
	v_mov_b32_e32 v60, v100
	v_mov_b32_e32 v61, v104
	v_pk_fma_f32 v[126:127], v[128:129], v[128:129], v[126:127]
	v_lshlrev_b32_e32 v120, 16, v63
	v_and_b32_e32 v121, 0xffff0000, v63
	v_lshlrev_b32_e32 v124, 16, v59
	v_mov_b32_e32 v62, v101
	v_mov_b32_e32 v63, v105
	v_pk_fma_f32 v[60:61], v[60:61], v[60:61], v[126:127]
	v_and_b32_e32 v125, 0xffff0000, v59
	v_mov_b32_e32 v56, v124
	v_mov_b32_e32 v57, v120
	v_pk_fma_f32 v[60:61], v[62:63], v[62:63], v[60:61]
	v_mov_b32_e32 v58, v125
	v_mov_b32_e32 v59, v121
	v_pk_fma_f32 v[56:57], v[56:57], v[56:57], v[60:61]
	v_and_b32_e32 v141, 31, v50
	v_pk_fma_f32 v[56:57], v[58:59], v[58:59], v[56:57]
	v_mul_u32_u24_e32 v173, 0x110, v141
	v_add_f32_e32 v56, v56, v57
	v_add_f32_e32 v56, v56, v98
	v_add_f32_e32 v56, v56, v99
	v_add_f32_e32 v56, v56, v94
	v_add_f32_e32 v56, v56, v95
	v_add_f32_e32 v56, v56, v92
	v_add_f32_e32 v92, v56, v93
	ds_bpermute_b32 v93, v139, v92
	global_load_dwordx4 v[56:59], v144, s[54:55] offset:400
	global_load_dwordx4 v[60:63], v144, s[54:55] offset:384
	v_mul_u32_u24_e32 v174, 0x88, v141
	s_waitcnt lgkmcnt(0)
	v_add_f32_e32 v92, v92, v93
	v_fmamk_f32 v92, v92, 0x3c000000, v156
	v_mul_f32_e32 v93, 0x4b800000, v92
	v_cmp_gt_f32_e32 vcc, s34, v92
	s_nop 1
	v_cndmask_b32_e32 v92, v92, v93, vcc
	v_rsq_f32_e32 v98, v92
	global_load_dwordx4 v[92:95], v144, s[54:55] offset:464
	global_load_dwordx4 v[126:129], v144, s[54:55] offset:448
	v_mul_f32_e32 v51, 0x45800000, v98
	v_cndmask_b32_e32 v51, v98, v51, vcc
	v_mul_f32_e32 v140, 0x3e0293ee, v51
	v_pk_mul_f32 v[98:99], v[140:141], v[132:133] op_sel_hi:[0,1]
	s_waitcnt vmcnt(6)
	v_pk_mul_f32 v[80:81], v[80:81], v[98:99]
	v_pk_mul_f32 v[48:49], v[140:141], v[48:49] op_sel_hi:[0,1]
	v_cvt_pk_bf16_f32 v98, v80, v81
	v_pk_mul_f32 v[80:81], v[140:141], v[130:131] op_sel_hi:[0,1]
	v_pk_mul_f32 v[80:81], v[82:83], v[80:81]
	v_pk_mul_f32 v[14:15], v[48:49], v[14:15]
	v_cvt_pk_bf16_f32 v99, v80, v81
	v_pk_mul_f32 v[80:81], v[140:141], v[100:101] op_sel_hi:[0,1]
	v_pk_mul_f32 v[64:65], v[64:65], v[80:81]
	v_mov_b32_e32 v51, v135
	v_cvt_pk_bf16_f32 v100, v64, v65
	v_pk_mul_f32 v[64:65], v[140:141], v[124:125] op_sel_hi:[0,1]
	v_pk_mul_f32 v[64:65], v[66:67], v[64:65]
	v_mov_b32_e32 v48, v135
	v_cvt_pk_bf16_f32 v101, v64, v65
	v_pk_mul_f32 v[64:65], v[140:141], v[102:103] op_sel_hi:[0,1]
	s_waitcnt vmcnt(4)
	v_pk_mul_f32 v[64:65], v[88:89], v[64:65]
	v_mov_b32_e32 v49, v135
	v_cvt_pk_bf16_f32 v102, v64, v65
	v_pk_mul_f32 v[64:65], v[140:141], v[122:123] op_sel_hi:[0,1]
	v_pk_mul_f32 v[64:65], v[90:91], v[64:65]
	s_nop 0
	v_cvt_pk_bf16_f32 v103, v64, v65
	v_pk_mul_f32 v[64:65], v[140:141], v[104:105] op_sel_hi:[0,1]
	v_pk_mul_f32 v[64:65], v[84:85], v[64:65]
	s_nop 0
	v_cvt_pk_bf16_f32 v104, v64, v65
	v_pk_mul_f32 v[64:65], v[140:141], v[120:121] op_sel_hi:[0,1]
	v_pk_mul_f32 v[64:65], v[86:87], v[64:65]
	s_nop 0
	v_cvt_pk_bf16_f32 v105, v64, v65
	v_pk_mul_f32 v[64:65], v[140:141], v[106:107] op_sel_hi:[0,1]
	v_pk_mul_f32 v[64:65], v[76:77], v[64:65]
	s_nop 0
	v_cvt_pk_bf16_f32 v106, v64, v65
	v_pk_mul_f32 v[64:65], v[140:141], v[118:119] op_sel_hi:[0,1]
	v_pk_mul_f32 v[64:65], v[64:65], v[78:79]
	s_nop 0
	v_cvt_pk_bf16_f32 v107, v64, v65
	v_pk_mul_f32 v[64:65], v[140:141], v[108:109] op_sel_hi:[0,1]
	v_pk_mul_f32 v[64:65], v[64:65], v[68:69]
	s_nop 0
	v_cvt_pk_bf16_f32 v108, v64, v65
	v_pk_mul_f32 v[64:65], v[140:141], v[116:117] op_sel_hi:[0,1]
	v_pk_mul_f32 v[64:65], v[64:65], v[70:71]
	s_nop 0
	v_cvt_pk_bf16_f32 v109, v64, v65
	v_pk_mul_f32 v[64:65], v[140:141], v[110:111] op_sel_hi:[0,1]
	v_pk_mul_f32 v[64:65], v[64:65], v[72:73]
	s_nop 0
	v_cvt_pk_bf16_f32 v110, v64, v65
	v_pk_mul_f32 v[64:65], v[140:141], v[114:115] op_sel_hi:[0,1]
	v_cvt_pk_bf16_f32 v114, v14, v15
	v_pk_mul_f32 v[14:15], v[140:141], v[46:47] op_sel_hi:[0,1]
	v_pk_mul_f32 v[14:15], v[14:15], v[16:17]
	v_pk_mul_f32 v[64:65], v[64:65], v[74:75]
	v_cvt_pk_bf16_f32 v115, v14, v15
	v_pk_mul_f32 v[14:15], v[140:141], v[44:45] op_sel_hi:[0,1]
	v_pk_mul_f32 v[10:11], v[14:15], v[10:11]
	v_add_u32_e32 v15, 0x200, v50
	v_cvt_pk_bf16_f32 v116, v10, v11
	v_pk_mul_f32 v[10:11], v[140:141], v[42:43] op_sel_hi:[0,1]
	v_pk_mul_f32 v[10:11], v[10:11], v[12:13]
	v_cvt_pk_bf16_f32 v111, v64, v65
	v_cvt_pk_bf16_f32 v117, v10, v11
	v_pk_mul_f32 v[10:11], v[140:141], v[40:41] op_sel_hi:[0,1]
	v_pk_mul_f32 v[6:7], v[10:11], v[6:7]
	v_ashrrev_i32_e32 v10, 31, v15
	v_cvt_pk_bf16_f32 v118, v6, v7
	v_pk_mul_f32 v[6:7], v[140:141], v[38:39] op_sel_hi:[0,1]
	v_pk_mul_f32 v[6:7], v[6:7], v[8:9]
	v_lshrrev_b32_e32 v10, 28, v10
	v_cvt_pk_bf16_f32 v119, v6, v7
	v_pk_mul_f32 v[6:7], v[140:141], v[36:37] op_sel_hi:[0,1]
	v_pk_mul_f32 v[2:3], v[6:7], v[2:3]
	v_add_u32_e32 v7, 0x100, v50
	v_cvt_pk_bf16_f32 v120, v2, v3
	v_pk_mul_f32 v[2:3], v[140:141], v[34:35] op_sel_hi:[0,1]
	v_pk_mul_f32 v[2:3], v[2:3], v[4:5]
	v_ashrrev_i32_e32 v6, 31, v7
	v_cvt_pk_bf16_f32 v121, v2, v3
	v_pk_mul_f32 v[2:3], v[140:141], v[32:33] op_sel_hi:[0,1]
	s_waitcnt vmcnt(2)
	v_pk_mul_f32 v[2:3], v[2:3], v[60:61]
	v_lshrrev_b32_e32 v6, 28, v6
	v_cvt_pk_bf16_f32 v122, v2, v3
	v_pk_mul_f32 v[2:3], v[140:141], v[30:31] op_sel_hi:[0,1]
	v_pk_mul_f32 v[2:3], v[2:3], v[62:63]
	v_add_u32_e32 v30, 0x300, v50
	v_cvt_pk_bf16_f32 v123, v2, v3
	v_pk_mul_f32 v[2:3], v[140:141], v[28:29] op_sel_hi:[0,1]
	v_pk_mul_f32 v[2:3], v[2:3], v[56:57]
	v_ashrrev_i32_e32 v14, 31, v30
	v_cvt_pk_bf16_f32 v124, v2, v3
	v_pk_mul_f32 v[2:3], v[140:141], v[26:27] op_sel_hi:[0,1]
	v_pk_mul_f32 v[2:3], v[2:3], v[58:59]
	v_add_u32_e32 v8, v7, v6
	v_cvt_pk_bf16_f32 v125, v2, v3
	v_pk_mul_f32 v[2:3], v[140:141], v[24:25] op_sel_hi:[0,1]
	s_waitcnt vmcnt(0)
	v_pk_mul_f32 v[2:3], v[2:3], v[126:127]
	v_lshrrev_b32_e32 v14, 28, v14
	v_cvt_pk_bf16_f32 v126, v2, v3
	v_pk_mul_f32 v[2:3], v[140:141], v[22:23] op_sel_hi:[0,1]
	v_pk_mul_f32 v[2:3], v[2:3], v[128:129]
	v_ashrrev_i32_e32 v6, 4, v8
	v_cvt_pk_bf16_f32 v127, v2, v3
	v_pk_mul_f32 v[2:3], v[140:141], v[20:21] op_sel_hi:[0,1]
	v_pk_mul_f32 v[2:3], v[2:3], v[92:93]
	v_and_b32_e32 v8, -16, v8
	v_cvt_pk_bf16_f32 v128, v2, v3
	v_pk_mul_f32 v[2:3], v[140:141], v[18:19] op_sel_hi:[0,1]
	v_pk_mul_f32 v[2:3], v[2:3], v[94:95]
	v_add_u32_e32 v12, v15, v10
	v_cvt_pk_bf16_f32 v129, v2, v3
	v_lshlrev_b32_e32 v2, 4, v50
	v_and_b32_e32 v160, 0x70, v2
	v_ashrrev_i32_e32 v2, 31, v50
	v_lshrrev_b32_e32 v2, 28, v2
	v_add_u32_e32 v3, v50, v2
	v_ashrrev_i32_e32 v2, 4, v3
	v_and_b32_e32 v3, -16, v3
	v_add_u32_e32 v16, v30, v14
	v_sub_u32_e32 v3, v50, v3
	v_sub_u32_e32 v11, v7, v8
	v_ashrrev_i32_e32 v10, 4, v12
	v_and_b32_e32 v12, -16, v12
	v_ashrrev_i32_e32 v14, 4, v16
	v_and_b32_e32 v16, -16, v16
	v_pk_mul_f32 v[64:65], v[140:141], v[112:113] op_sel_hi:[0,1]
	v_lshlrev_b32_e32 v4, 3, v3
	v_lshlrev_b32_e32 v8, 3, v11
	v_sub_u32_e32 v34, v15, v12
	v_sub_u32_e32 v35, v30, v16
	v_ashrrev_i32_e32 v18, 3, v50
	v_ashrrev_i32_e32 v22, 3, v7
	v_ashrrev_i32_e32 v26, 3, v15
	v_ashrrev_i32_e32 v30, 3, v30
	v_lshlrev_b32_e32 v162, 4, v3
	v_lshlrev_b32_e32 v164, 4, v11
	v_ashrrev_i32_e32 v15, 31, v14
	v_ashrrev_i32_e32 v11, 31, v10
	v_ashrrev_i32_e32 v7, 31, v6
	v_ashrrev_i32_e32 v3, 31, v2
	v_pk_mul_f32 v[52:53], v[64:65], v[52:53]
	v_ashrrev_i32_e32 v19, 31, v18
	v_ashrrev_i32_e32 v23, 31, v22
	v_ashrrev_i32_e32 v27, 31, v26
	v_ashrrev_i32_e32 v31, 31, v30
	v_mul_lo_u32 v161, v2, s35
	v_mul_lo_u32 v163, v6, s35
	v_mul_lo_u32 v165, v10, s35
	v_mul_lo_u32 v167, v14, s35
	v_lshlrev_b64 v[14:15], 10, v[14:15]
	v_lshlrev_b64 v[10:11], 10, v[10:11]
	v_lshlrev_b64 v[6:7], 10, v[6:7]
	v_lshlrev_b64 v[2:3], 10, v[2:3]
	v_cvt_pk_bf16_f32 v112, v52, v53
	v_pk_mul_f32 v[52:53], v[140:141], v[96:97] op_sel_hi:[0,1]
	v_lshlrev_b32_e32 v12, 3, v34
	v_lshlrev_b32_e32 v16, 3, v35
	v_lshlrev_b64 v[20:21], 9, v[18:19]
	v_lshlrev_b64 v[24:25], 9, v[22:23]
	v_lshlrev_b64 v[28:29], 9, v[26:27]
	v_lshlrev_b64 v[32:33], 9, v[30:31]
	v_lshl_add_u64 v[14:15], s[8:9], 0, v[14:15]
	v_lshl_add_u64 v[10:11], s[8:9], 0, v[10:11]
	v_lshl_add_u64 v[6:7], s[8:9], 0, v[6:7]
	v_lshl_add_u64 v[2:3], s[8:9], 0, v[2:3]
	v_pk_mul_f32 v[52:53], v[52:53], v[54:55]
	v_ashrrev_i32_e32 v5, 31, v4
	v_ashrrev_i32_e32 v9, 31, v8
	v_ashrrev_i32_e32 v13, 31, v12
	v_ashrrev_i32_e32 v17, 31, v16
	v_lshl_add_u64 v[140:141], s[10:11], 0, v[20:21]
	v_lshl_add_u64 v[142:143], s[10:11], 0, v[24:25]
	v_lshl_add_u64 v[144:145], s[10:11], 0, v[28:29]
	v_lshl_add_u64 v[146:147], s[10:11], 0, v[32:33]
	v_or_b32_e32 v14, s41, v14
	v_or_b32_e32 v10, s41, v10
	v_or_b32_e32 v6, s41, v6
	v_or_b32_e32 v2, s41, v2
	v_cvt_pk_bf16_f32 v113, v52, v53
	v_lshlrev_b32_e32 v166, 4, v34
	v_lshlrev_b32_e32 v168, 4, v35
	v_mul_lo_u32 v169, v18, s38
	v_mul_lo_u32 v170, v22, s38
	v_mul_lo_u32 v171, v26, s38
	v_mul_lo_u32 v172, v30, s38
	v_or_b32_e32 v140, v140, v160
	v_or_b32_e32 v142, v142, v160
	v_or_b32_e32 v144, v144, v160
	v_or_b32_e32 v146, v146, v160
	v_lshl_add_u64 v[148:149], v[16:17], 1, v[14:15]
	v_lshl_add_u64 v[150:151], v[12:13], 1, v[10:11]
	v_lshl_add_u64 v[152:153], v[8:9], 1, v[6:7]
	v_lshl_add_u64 v[154:155], v[4:5], 1, v[2:3]
	s_mov_b32 s8, 0
	v_mov_b32_e32 v50, 0
	v_mov_b32_e32 v52, v135
	v_mov_b32_e32 v53, v135
	v_mov_b32_e32 v54, v135
	v_mov_b32_e32 v55, v135
	v_mov_b32_e32 v56, v135
	v_mov_b32_e32 v57, v135
	v_mov_b32_e32 v58, v135
	v_mov_b32_e32 v59, v135
	v_mov_b32_e32 v60, v135
	v_mov_b32_e32 v61, v135
	v_mov_b32_e32 v62, v135
	v_mov_b32_e32 v63, v135
	v_mov_b32_e32 v64, v135
	v_mov_b32_e32 v65, v135
	v_mov_b32_e32 v34, 0
	v_mov_b32_e32 v35, v135
	v_mov_b32_e32 v36, v135
	v_mov_b32_e32 v37, v135
	v_mov_b32_e32 v38, v135
	v_mov_b32_e32 v39, v135
	v_mov_b32_e32 v40, v135
	v_mov_b32_e32 v41, v135
	v_mov_b32_e32 v42, v135
	v_mov_b32_e32 v43, v135
	v_mov_b32_e32 v44, v135
	v_mov_b32_e32 v45, v135
	v_mov_b32_e32 v46, v135
	v_mov_b32_e32 v47, v135
	v_mov_b32_e32 v18, 0
	v_mov_b32_e32 v19, v135
	v_mov_b32_e32 v20, v135
	v_mov_b32_e32 v21, v135
	v_mov_b32_e32 v22, v135
	v_mov_b32_e32 v23, v135
	v_mov_b32_e32 v24, v135
	v_mov_b32_e32 v25, v135
	v_mov_b32_e32 v26, v135
	v_mov_b32_e32 v27, v135
	v_mov_b32_e32 v28, v135
	v_mov_b32_e32 v29, v135
	v_mov_b32_e32 v30, v135
	v_mov_b32_e32 v31, v135
	v_mov_b32_e32 v32, v135
	v_mov_b32_e32 v33, v135
	v_mov_b32_e32 v2, 0
	v_mov_b32_e32 v3, v135
	v_mov_b32_e32 v4, v135
	v_mov_b32_e32 v5, v135
	v_mov_b32_e32 v6, v135
	v_mov_b32_e32 v7, v135
	v_mov_b32_e32 v8, v135
	v_mov_b32_e32 v9, v135
	v_mov_b32_e32 v10, v135
	v_mov_b32_e32 v11, v135
	v_mov_b32_e32 v12, v135
	v_mov_b32_e32 v13, v135
	v_mov_b32_e32 v14, v135
	v_mov_b32_e32 v15, v135
	v_mov_b32_e32 v16, v135
	v_mov_b32_e32 v17, v135
	v_lshl_add_u64 v[80:81], s[78:79], 0, v[146:147]
	v_add_co_u32_e32 v94, vcc, s40, v80
	v_lshl_add_u64 v[76:77], s[78:79], 0, v[144:145]
	s_nop 0
	v_addc_co_u32_e32 v95, vcc, 0, v81, vcc
	v_add_co_u32_e32 v90, vcc, s40, v76
	v_lshl_add_u64 v[72:73], s[78:79], 0, v[142:143]
	s_nop 0
	v_addc_co_u32_e32 v91, vcc, 0, v77, vcc
	v_add_co_u32_e32 v86, vcc, s40, v72
	v_lshl_add_u64 v[68:69], s[78:79], 0, v[140:141]
	s_nop 0
	v_addc_co_u32_e32 v87, vcc, 0, v73, vcc
	v_add_co_u32_e32 v82, vcc, s40, v68
	v_lshl_add_u64 v[66:67], s[78:79], 0, v[154:155]
	v_lshl_add_u64 v[70:71], s[78:79], 0, v[152:153]
	v_lshl_add_u64 v[74:75], s[78:79], 0, v[150:151]
	v_lshl_add_u64 v[78:79], s[78:79], 0, v[148:149]
	v_addc_co_u32_e32 v83, vcc, 0, v69, vcc
	global_load_dwordx4 v[220:223], v[66:67], off
	s_nop 0
	global_load_dwordx4 v[224:227], v[70:71], off
	s_nop 0
	global_load_dwordx4 v[228:231], v[74:75], off
	s_nop 0
	global_load_dwordx4 v[232:235], v[78:79], off
	s_nop 0
	global_load_dwordx4 v[236:239], v[82:83], off
	s_nop 0
	global_load_dwordx4 v[240:243], v[86:87], off
	s_nop 0
	global_load_dwordx4 v[244:247], v[90:91], off
	s_nop 0
	global_load_dwordx4 v[248:251], v[94:95], off
	v_lshl_add_u64 v[140:141], v[140:141], 0, s[0:1]
	v_lshl_add_u64 v[142:143], v[142:143], 0, s[0:1]
	v_lshl_add_u64 v[144:145], v[144:145], 0, s[0:1]
	v_lshl_add_u64 v[146:147], v[146:147], 0, s[0:1]
	v_lshl_add_u64 v[148:149], v[148:149], 0, s[6:7]
	v_lshl_add_u64 v[150:151], v[150:151], 0, s[6:7]
	v_lshl_add_u64 v[152:153], v[152:153], 0, s[6:7]
	v_lshl_add_u64 v[154:155], v[154:155], 0, s[6:7]
.LBB0_831:
	s_bitcmp1_b32 s8, 0
	s_cselect_b32 s9, 0x8800, 0
	s_add_i32 s9, s13, s9
	v_add3_u32 v130, s9, v161, v162
	v_add3_u32 v131, s9, v163, v164
	v_add3_u32 v132, s9, v165, v166
	v_add3_u32 v133, s9, v167, v168
	v_add_u32_e32 v176, s9, v160
	v_add3_u32 v177, s9, v134, v173
	v_add3_u32 v179, v176, v169, s39
	v_add3_u32 v180, v176, v170, s39
	v_add3_u32 v181, v176, v171, s39
	v_add3_u32 v176, v176, v172, s39
	s_add_i32 s8, s8, 1
	s_cmp_lg_u32 s8, 4
	s_waitcnt vmcnt(7)
	ds_write_b128 v130, v[220:223]
	s_waitcnt vmcnt(6)
	ds_write_b128 v131, v[224:227]
	s_waitcnt vmcnt(5)
	ds_write_b128 v132, v[228:231]
	s_waitcnt vmcnt(4)
	ds_write_b128 v133, v[232:235]
	s_waitcnt vmcnt(3)
	ds_write2_b64 v179, v[236:237], v[238:239] offset1:1
	s_waitcnt vmcnt(2)
	ds_write2_b64 v180, v[240:241], v[242:243] offset1:1
	s_waitcnt vmcnt(1)
	ds_write2_b64 v181, v[244:245], v[246:247] offset1:1
	s_waitcnt vmcnt(0)
	ds_write2_b64 v176, v[248:249], v[250:251] offset1:1
	s_waitcnt lgkmcnt(0)
	s_barrier
	s_cbranch_scc0 .Lxa_noload
	v_lshl_add_u64 v[80:81], s[78:79], 0, v[146:147]
	v_add_co_u32_e32 v94, vcc, s40, v80
	v_lshl_add_u64 v[76:77], s[78:79], 0, v[144:145]
	s_nop 0
	v_addc_co_u32_e32 v95, vcc, 0, v81, vcc
	v_add_co_u32_e32 v90, vcc, s40, v76
	v_lshl_add_u64 v[72:73], s[78:79], 0, v[142:143]
	s_nop 0
	v_addc_co_u32_e32 v91, vcc, 0, v77, vcc
	v_add_co_u32_e32 v86, vcc, s40, v72
	v_lshl_add_u64 v[68:69], s[78:79], 0, v[140:141]
	s_nop 0
	v_addc_co_u32_e32 v87, vcc, 0, v73, vcc
	v_add_co_u32_e32 v82, vcc, s40, v68
	v_lshl_add_u64 v[66:67], s[78:79], 0, v[154:155]
	v_lshl_add_u64 v[70:71], s[78:79], 0, v[152:153]
	v_lshl_add_u64 v[74:75], s[78:79], 0, v[150:151]
	v_lshl_add_u64 v[78:79], s[78:79], 0, v[148:149]
	v_addc_co_u32_e32 v83, vcc, 0, v69, vcc
	global_load_dwordx4 v[220:223], v[66:67], off
	s_nop 0
	global_load_dwordx4 v[224:227], v[70:71], off
	s_nop 0
	global_load_dwordx4 v[228:231], v[74:75], off
	s_nop 0
	global_load_dwordx4 v[232:235], v[78:79], off
	s_nop 0
	global_load_dwordx4 v[236:239], v[82:83], off
	s_nop 0
	global_load_dwordx4 v[240:243], v[86:87], off
	s_nop 0
	global_load_dwordx4 v[244:247], v[90:91], off
	s_nop 0
	global_load_dwordx4 v[248:251], v[94:95], off
	v_lshl_add_u64 v[140:141], v[140:141], 0, s[0:1]
	v_lshl_add_u64 v[142:143], v[142:143], 0, s[0:1]
	v_lshl_add_u64 v[144:145], v[144:145], 0, s[0:1]
	v_lshl_add_u64 v[146:147], v[146:147], 0, s[0:1]
	v_lshl_add_u64 v[148:149], v[148:149], 0, s[6:7]
	v_lshl_add_u64 v[150:151], v[150:151], 0, s[6:7]
	v_lshl_add_u64 v[152:153], v[152:153], 0, s[6:7]
	v_lshl_add_u64 v[154:155], v[154:155], 0, s[6:7]
.Lxa_noload:
	ds_read_b128 v[66:69], v177
	ds_read_b128 v[130:133], v177 offset:32
	s_waitcnt lgkmcnt(1)
	v_mfma_f32_32x32x16_bf16 v[82:97], v[66:69], v[98:101], 0
	ds_read_b128 v[66:69], v177 offset:8704
	ds_read_b128 v[180:183], v177 offset:8736
	v_mov_b32_e32 v176, v178
	s_waitcnt lgkmcnt(1)
	v_mfma_f32_32x32x16_bf16 v[66:81], v[66:69], v[98:101], 0
	v_mfma_f32_32x32x16_bf16 v[82:97], v[130:133], v[102:105], v[82:97]
	s_waitcnt lgkmcnt(0)
	v_mfma_f32_32x32x16_bf16 v[66:81], v[180:183], v[102:105], v[66:81]
	ds_read_b128 v[130:133], v177 offset:64
	ds_read_b128 v[180:183], v177 offset:96
	s_waitcnt lgkmcnt(1)
	v_mfma_f32_32x32x16_bf16 v[82:97], v[130:133], v[106:109], v[82:97]
	ds_read_b128 v[130:133], v177 offset:8768
	ds_read_b128 v[184:187], v177 offset:8800
	s_waitcnt lgkmcnt(1)
	v_mfma_f32_32x32x16_bf16 v[66:81], v[130:133], v[106:109], v[66:81]
	v_mfma_f32_32x32x16_bf16 v[82:97], v[180:183], v[110:113], v[82:97]
	ds_read_b128 v[130:133], v177 offset:128
	ds_read_b128 v[180:183], v177 offset:160
	s_waitcnt lgkmcnt(2)
	v_mfma_f32_32x32x16_bf16 v[66:81], v[184:187], v[110:113], v[66:81]
	s_waitcnt lgkmcnt(1)
	v_mfma_f32_32x32x16_bf16 v[82:97], v[130:133], v[114:117], v[82:97]
	ds_read_b128 v[184:187], v177 offset:8832
	ds_read_b128 v[130:133], v177 offset:8864
	s_waitcnt lgkmcnt(1)
	v_mfma_f32_32x32x16_bf16 v[66:81], v[184:187], v[114:117], v[66:81]
	v_mfma_f32_32x32x16_bf16 v[82:97], v[180:183], v[118:121], v[82:97]
	s_waitcnt lgkmcnt(0)
	v_mfma_f32_32x32x16_bf16 v[66:81], v[130:133], v[118:121], v[66:81]
	ds_read_b128 v[130:133], v177 offset:192
	ds_read_b128 v[178:181], v177 offset:224
	s_waitcnt lgkmcnt(1)
	v_mfma_f32_32x32x16_bf16 v[82:97], v[130:133], v[122:125], v[82:97]
	ds_read_b128 v[130:133], v177 offset:8896
	ds_read_b128 v[182:185], v177 offset:8928
	s_waitcnt lgkmcnt(1)
	v_mfma_f32_32x32x16_bf16 v[66:81], v[130:133], v[122:125], v[66:81]
	v_add3_u32 v130, s9, v138, v174
	v_add_u32_e32 v177, 0x4000, v130
	v_add_u32_e32 v203, 0x5000, v130
	v_add_u32_e32 v204, 0x6000, v130
	v_add_u32_e32 v205, 0x7000, v130
	v_mfma_f32_32x32x16_bf16 v[82:97], v[178:181], v[126:129], v[82:97]
	ds_read2_b64 v[130:133], v177 offset0:128 offset1:130
	ds_read2_b64 v[178:181], v177 offset0:132 offset1:134
	ds_read2_b64 v[186:189], v203 offset0:160 offset1:162
	ds_read2_b64 v[190:193], v204 offset0:192 offset1:194
	ds_read2_b64 v[194:197], v205 offset0:224 offset1:226
	ds_read2_b64 v[198:201], v203 offset0:164 offset1:166
	s_waitcnt lgkmcnt(6)
	v_mfma_f32_32x32x16_bf16 v[66:81], v[182:185], v[126:129], v[66:81]
	s_nop 3
	v_max_f32_e32 v182, v83, v83
	v_max_f32_e32 v183, v82, v82
	v_max_f32_e32 v182, v183, v182
	v_max3_f32 v182, v182, v84, v85
	v_max3_f32 v182, v182, v86, v87
	v_max3_f32 v182, v182, v88, v89
	v_max3_f32 v182, v182, v90, v91
	v_max3_f32 v182, v182, v92, v93
	v_max3_f32 v182, v182, v94, v95
	v_max3_f32 v182, v182, v96, v97
	v_max3_f32 v182, v182, v66, v67
	v_max3_f32 v182, v182, v68, v69
	v_max3_f32 v182, v182, v70, v71
	v_max3_f32 v182, v182, v72, v73
	v_max3_f32 v182, v182, v74, v75
	v_max3_f32 v182, v182, v76, v77
	v_max3_f32 v182, v182, v78, v79
	v_max3_f32 v182, v182, v80, v81
	ds_bpermute_b32 v183, v139, v182
	s_waitcnt lgkmcnt(0)
	v_max3_f32 v206, v175, v182, v183
	v_sub_f32_e32 v175, v175, v206
	v_sub_f32_e32 v82, v82, v206
	v_sub_f32_e32 v83, v83, v206
	v_sub_f32_e32 v84, v84, v206
	v_sub_f32_e32 v85, v85, v206
	v_sub_f32_e32 v86, v86, v206
	v_sub_f32_e32 v87, v87, v206
	v_sub_f32_e32 v88, v88, v206
	v_sub_f32_e32 v89, v89, v206
	v_exp_f32_e32 v202, v175
	v_exp_f32_e32 v207, v82
	v_exp_f32_e32 v208, v83
	v_exp_f32_e32 v209, v84
	v_exp_f32_e32 v210, v85
	v_exp_f32_e32 v211, v86
	v_exp_f32_e32 v212, v87
	v_exp_f32_e32 v213, v88
	v_exp_f32_e32 v214, v89
	v_pk_mul_f32 v[64:65], v[64:65], v[202:203] op_sel_hi:[1,0]
	v_pk_mul_f32 v[62:63], v[62:63], v[202:203] op_sel_hi:[1,0]
	v_pk_mul_f32 v[60:61], v[60:61], v[202:203] op_sel_hi:[1,0]
	v_pk_mul_f32 v[58:59], v[58:59], v[202:203] op_sel_hi:[1,0]
	v_pk_mul_f32 v[56:57], v[56:57], v[202:203] op_sel_hi:[1,0]
	v_pk_mul_f32 v[54:55], v[54:55], v[202:203] op_sel_hi:[1,0]
	v_pk_mul_f32 v[52:53], v[52:53], v[202:203] op_sel_hi:[1,0]
	v_pk_mul_f32 v[50:51], v[50:51], v[202:203] op_sel_hi:[1,0]
	v_cvt_pk_bf16_f32 v82, v207, v208
	v_cvt_pk_bf16_f32 v83, v209, v210
	v_cvt_pk_bf16_f32 v84, v211, v212
	v_cvt_pk_bf16_f32 v85, v213, v214
	v_pk_mul_f32 v[48:49], v[48:49], v[202:203] op_sel_hi:[1,0]
	v_pk_mul_f32 v[46:47], v[46:47], v[202:203] op_sel_hi:[1,0]
	v_pk_mul_f32 v[44:45], v[44:45], v[202:203] op_sel_hi:[1,0]
	v_mfma_f32_32x32x16_bf16 v[50:65], v[130:133], v[82:85], v[50:65]
	v_mul_f32_e64 v42, v42, v202
	v_mul_f32_e64 v43, v43, v202
	v_mul_f32_e64 v40, v40, v202
	v_mul_f32_e64 v41, v41, v202
	v_mul_f32_e64 v38, v38, v202
	v_mul_f32_e64 v39, v39, v202
	v_pk_mul_f32 v[36:37], v[36:37], v[202:203] op_sel_hi:[1,0]
	v_pk_mul_f32 v[34:35], v[34:35], v[202:203] op_sel_hi:[1,0]
	v_pk_mul_f32 v[32:33], v[32:33], v[202:203] op_sel_hi:[1,0]
	v_pk_mul_f32 v[30:31], v[30:31], v[202:203] op_sel_hi:[1,0]
	v_pk_mul_f32 v[28:29], v[28:29], v[202:203] op_sel_hi:[1,0]
	v_pk_mul_f32 v[26:27], v[26:27], v[202:203] op_sel_hi:[1,0]
	v_pk_mul_f32 v[24:25], v[24:25], v[202:203] op_sel_hi:[1,0]
	v_pk_mul_f32 v[22:23], v[22:23], v[202:203] op_sel_hi:[1,0]
	v_pk_mul_f32 v[20:21], v[20:21], v[202:203] op_sel_hi:[1,0]
	v_pk_mul_f32 v[18:19], v[18:19], v[202:203] op_sel_hi:[1,0]
	v_pk_mul_f32 v[16:17], v[16:17], v[202:203] op_sel_hi:[1,0]
	v_pk_mul_f32 v[14:15], v[14:15], v[202:203] op_sel_hi:[1,0]
	v_pk_mul_f32 v[12:13], v[12:13], v[202:203] op_sel_hi:[1,0]
	v_pk_mul_f32 v[10:11], v[10:11], v[202:203] op_sel_hi:[1,0]
	v_pk_mul_f32 v[8:9], v[8:9], v[202:203] op_sel_hi:[1,0]
	v_pk_mul_f32 v[6:7], v[6:7], v[202:203] op_sel_hi:[1,0]
	v_pk_mul_f32 v[4:5], v[4:5], v[202:203] op_sel_hi:[1,0]
	v_pk_mul_f32 v[2:3], v[2:3], v[202:203] op_sel_hi:[1,0]
	v_mfma_f32_32x32x16_bf16 v[34:49], v[186:189], v[82:85], v[34:49]
	v_sub_f32_e32 v90, v90, v206
	v_sub_f32_e32 v91, v91, v206
	v_sub_f32_e32 v92, v92, v206
	v_sub_f32_e32 v93, v93, v206
	v_sub_f32_e32 v94, v94, v206
	v_sub_f32_e32 v95, v95, v206
	v_sub_f32_e32 v96, v96, v206
	v_mfma_f32_32x32x16_bf16 v[18:33], v[190:193], v[82:85], v[18:33]
	v_sub_f32_e32 v97, v97, v206
	v_exp_f32_e32 v215, v90
	v_exp_f32_e32 v216, v91
	v_exp_f32_e32 v217, v92
	v_exp_f32_e32 v218, v93
	v_exp_f32_e32 v219, v94
	v_sub_f32_e32 v66, v66, v206
	v_mfma_f32_32x32x16_bf16 v[2:17], v[194:197], v[82:85], v[2:17]
	v_exp_f32_e32 v194, v95
	v_exp_f32_e32 v195, v96
	v_exp_f32_e32 v196, v97
	v_cvt_pk_bf16_f32 v82, v215, v216
	v_cvt_pk_bf16_f32 v83, v217, v218
	v_cvt_pk_bf16_f32 v84, v219, v194
	v_cvt_pk_bf16_f32 v85, v195, v196
	v_sub_f32_e32 v67, v67, v206
	v_sub_f32_e32 v68, v68, v206
	v_mfma_f32_32x32x16_bf16 v[50:65], v[178:181], v[82:85], v[50:65]
	ds_read2_b64 v[86:89], v204 offset0:196 offset1:198
	ds_read2_b64 v[90:93], v205 offset0:228 offset1:230
	ds_read2_b64 v[94:97], v177 offset0:136 offset1:138
	ds_read2_b64 v[130:133], v203 offset0:168 offset1:170
	ds_read2_b64 v[178:181], v204 offset0:200 offset1:202
	ds_read2_b64 v[182:185], v205 offset0:232 offset1:234
	ds_read2_b64 v[186:189], v177 offset0:140 offset1:142
	v_sub_f32_e32 v69, v69, v206
	v_sub_f32_e32 v70, v70, v206
	v_sub_f32_e32 v71, v71, v206
	v_sub_f32_e32 v72, v72, v206
	v_sub_f32_e32 v73, v73, v206
	v_exp_f32_e32 v177, v70
	v_mfma_f32_32x32x16_bf16 v[34:49], v[198:201], v[82:85], v[34:49]
	ds_read2_b64 v[190:193], v203 offset0:172 offset1:174
	v_sub_f32_e32 v74, v74, v206
	v_sub_f32_e32 v75, v75, v206
	v_sub_f32_e32 v76, v76, v206
	v_sub_f32_e32 v77, v77, v206
	v_sub_f32_e32 v78, v78, v206
	v_sub_f32_e32 v79, v79, v206
	s_waitcnt lgkmcnt(7)
	v_mfma_f32_32x32x16_bf16 v[18:33], v[86:89], v[82:85], v[18:33]
	v_exp_f32_e32 v86, v66
	v_exp_f32_e32 v87, v67
	v_exp_f32_e32 v88, v68
	v_exp_f32_e32 v89, v69
	v_sub_f32_e32 v80, v80, v206
	v_cvt_pk_bf16_f32 v66, v86, v87
	v_sub_f32_e32 v81, v81, v206
	s_waitcnt lgkmcnt(6)
	v_mfma_f32_32x32x16_bf16 v[2:17], v[90:93], v[82:85], v[2:17]
	v_exp_f32_e32 v90, v71
	v_exp_f32_e32 v91, v72
	v_exp_f32_e32 v92, v73
	v_cvt_pk_bf16_f32 v67, v88, v89
	v_cvt_pk_bf16_f32 v68, v177, v90
	ds_read2_b64 v[70:73], v204 offset0:204 offset1:206
	ds_read2_b64 v[82:85], v205 offset0:236 offset1:238
	v_cvt_pk_bf16_f32 v69, v91, v92
	v_exp_f32_e32 v93, v74
	v_exp_f32_e32 v78, v78
	s_waitcnt lgkmcnt(7)
	v_mfma_f32_32x32x16_bf16 v[50:65], v[94:97], v[66:69], v[50:65]
	v_add_f32_e32 v97, 0, v207
	v_exp_f32_e32 v94, v75
	v_exp_f32_e32 v95, v76
	v_exp_f32_e32 v96, v77
	v_exp_f32_e32 v79, v79
	v_exp_f32_e32 v80, v80
	v_exp_f32_e32 v81, v81
	s_waitcnt lgkmcnt(6)
	v_mfma_f32_32x32x16_bf16 v[34:49], v[130:133], v[66:69], v[34:49]
	v_cvt_pk_bf16_f32 v74, v93, v94
	v_cvt_pk_bf16_f32 v75, v95, v96
	v_cvt_pk_bf16_f32 v76, v78, v79
	v_cvt_pk_bf16_f32 v77, v80, v81
	v_mov_b32_e32 v175, v206
	s_waitcnt lgkmcnt(5)
	v_mfma_f32_32x32x16_bf16 v[18:33], v[178:181], v[66:69], v[18:33]
	s_waitcnt lgkmcnt(4)
	v_mfma_f32_32x32x16_bf16 v[2:17], v[182:185], v[66:69], v[2:17]
	v_add_f32_e32 v66, v208, v97
	v_add_f32_e32 v66, v209, v66
	v_add_f32_e32 v66, v210, v66
	v_add_f32_e32 v66, v211, v66
	v_add_f32_e32 v66, v212, v66
	v_add_f32_e32 v66, v213, v66
	v_add_f32_e32 v66, v214, v66
	v_add_f32_e32 v66, v215, v66
	v_add_f32_e32 v66, v216, v66
	v_add_f32_e32 v66, v217, v66
	v_add_f32_e32 v66, v218, v66
	v_add_f32_e32 v66, v219, v66
	v_add_f32_e32 v66, v194, v66
	v_add_f32_e32 v66, v195, v66
	v_add_f32_e32 v66, v196, v66
	v_add_f32_e32 v66, v86, v66
	v_add_f32_e32 v66, v87, v66
	v_add_f32_e32 v66, v88, v66
	v_add_f32_e32 v66, v89, v66
	v_add_f32_e32 v66, v177, v66
	v_add_f32_e32 v66, v90, v66
	v_add_f32_e32 v66, v91, v66
	v_add_f32_e32 v66, v92, v66
	v_add_f32_e32 v66, v93, v66
	s_waitcnt lgkmcnt(3)
	v_mfma_f32_32x32x16_bf16 v[50:65], v[186:189], v[74:77], v[50:65]
	v_add_f32_e32 v66, v94, v66
	v_add_f32_e32 v66, v95, v66
	v_add_f32_e32 v66, v96, v66
	v_add_f32_e32 v66, v78, v66
	v_add_f32_e32 v66, v79, v66
	v_add_f32_e32 v66, v80, v66
	v_add_f32_e32 v178, v81, v66
	s_waitcnt lgkmcnt(2)
	v_mfma_f32_32x32x16_bf16 v[34:49], v[190:193], v[74:77], v[34:49]
	v_fmac_f32_e32 v178, v176, v202
	s_waitcnt lgkmcnt(1)
	v_mfma_f32_32x32x16_bf16 v[18:33], v[70:73], v[74:77], v[18:33]
	s_waitcnt lgkmcnt(0)
	v_mfma_f32_32x32x16_bf16 v[2:17], v[82:85], v[74:77], v[2:17]
	s_cbranch_scc1 .LBB0_831
	ds_bpermute_b32 v66, v139, v178
	v_mov_b32_e32 v139, v135
	s_add_i32 s12, s12, s3
	s_sub_i32 s14, s14, s3
	s_cmpk_gt_i32 s12, 0x3ff
	s_waitcnt lgkmcnt(0)
	v_add_f32_e32 v68, v178, v66
	v_div_scale_f32 v69, s[8:9], v68, v68, 1.0
	v_rcp_f32_e32 v70, v69
	v_div_scale_f32 v71, vcc, 1.0, v68, 1.0
	v_lshl_add_u64 v[66:67], v[136:137], 0, v[138:139]
	v_fma_f32 v72, -v69, v70, 1.0
	v_fmac_f32_e32 v70, v72, v70
	v_mul_f32_e32 v72, v71, v70
	v_fma_f32 v73, -v69, v72, v71
	v_fmac_f32_e32 v72, v73, v70
	v_fma_f32 v69, -v69, v72, v71
	v_div_fmas_f32 v69, v69, v70, v72
	v_div_fixup_f32 v68, v69, v68, 1.0
	v_pk_mul_f32 v[50:51], v[50:51], v[68:69] op_sel_hi:[1,0]
	v_pk_mul_f32 v[52:53], v[52:53], v[68:69] op_sel_hi:[1,0]
	v_pk_mul_f32 v[34:35], v[34:35], v[68:69] op_sel_hi:[1,0]
	v_pk_mul_f32 v[36:37], v[36:37], v[68:69] op_sel_hi:[1,0]
	v_pk_mul_f32 v[18:19], v[18:19], v[68:69] op_sel_hi:[1,0]
	v_pk_mul_f32 v[20:21], v[20:21], v[68:69] op_sel_hi:[1,0]
	v_pk_mul_f32 v[2:3], v[2:3], v[68:69] op_sel_hi:[1,0]
	v_pk_mul_f32 v[4:5], v[4:5], v[68:69] op_sel_hi:[1,0]
	v_cvt_pk_bf16_f32 v50, v50, v51
	v_cvt_pk_bf16_f32 v51, v52, v53
	v_cvt_pk_bf16_f32 v34, v34, v35
	v_cvt_pk_bf16_f32 v35, v36, v37
	v_cvt_pk_bf16_f32 v18, v18, v19
	v_cvt_pk_bf16_f32 v19, v20, v21
	v_cvt_pk_bf16_f32 v2, v2, v3
	v_cvt_pk_bf16_f32 v3, v4, v5
	global_store_dwordx2 v[66:67], v[50:51], off
	v_pk_mul_f32 v[50:51], v[54:55], v[68:69] op_sel_hi:[1,0]
	v_pk_mul_f32 v[52:53], v[56:57], v[68:69] op_sel_hi:[1,0]
	global_store_dwordx2 v[66:67], v[34:35], off offset:64
	v_pk_mul_f32 v[34:35], v[38:39], v[68:69] op_sel_hi:[1,0]
	v_pk_mul_f32 v[36:37], v[40:41], v[68:69] op_sel_hi:[1,0]
	global_store_dwordx2 v[66:67], v[18:19], off offset:128
	v_pk_mul_f32 v[18:19], v[22:23], v[68:69] op_sel_hi:[1,0]
	v_pk_mul_f32 v[20:21], v[24:25], v[68:69] op_sel_hi:[1,0]
	global_store_dwordx2 v[66:67], v[2:3], off offset:192
	v_pk_mul_f32 v[2:3], v[6:7], v[68:69] op_sel_hi:[1,0]
	v_pk_mul_f32 v[4:5], v[8:9], v[68:69] op_sel_hi:[1,0]
	v_cvt_pk_bf16_f32 v50, v50, v51
	v_cvt_pk_bf16_f32 v51, v52, v53
	v_cvt_pk_bf16_f32 v34, v34, v35
	v_cvt_pk_bf16_f32 v35, v36, v37
	v_cvt_pk_bf16_f32 v18, v18, v19
	v_cvt_pk_bf16_f32 v19, v20, v21
	v_cvt_pk_bf16_f32 v2, v2, v3
	v_cvt_pk_bf16_f32 v3, v4, v5
	global_store_dwordx2 v[66:67], v[50:51], off offset:16
	v_pk_mul_f32 v[50:51], v[58:59], v[68:69] op_sel_hi:[1,0]
	v_pk_mul_f32 v[52:53], v[60:61], v[68:69] op_sel_hi:[1,0]
	global_store_dwordx2 v[66:67], v[34:35], off offset:80
	v_pk_mul_f32 v[34:35], v[42:43], v[68:69] op_sel_hi:[1,0]
	v_pk_mul_f32 v[36:37], v[44:45], v[68:69] op_sel_hi:[1,0]
	global_store_dwordx2 v[66:67], v[18:19], off offset:144
	v_pk_mul_f32 v[18:19], v[26:27], v[68:69] op_sel_hi:[1,0]
	v_pk_mul_f32 v[20:21], v[28:29], v[68:69] op_sel_hi:[1,0]
	global_store_dwordx2 v[66:67], v[2:3], off offset:208
	v_pk_mul_f32 v[2:3], v[10:11], v[68:69] op_sel_hi:[1,0]
	v_pk_mul_f32 v[4:5], v[12:13], v[68:69] op_sel_hi:[1,0]
	v_cvt_pk_bf16_f32 v50, v50, v51
	v_cvt_pk_bf16_f32 v51, v52, v53
	v_cvt_pk_bf16_f32 v34, v34, v35
	v_cvt_pk_bf16_f32 v35, v36, v37
	v_cvt_pk_bf16_f32 v18, v18, v19
	v_cvt_pk_bf16_f32 v19, v20, v21
	v_cvt_pk_bf16_f32 v2, v2, v3
	v_cvt_pk_bf16_f32 v3, v4, v5
	global_store_dwordx2 v[66:67], v[50:51], off offset:32
	v_pk_mul_f32 v[50:51], v[62:63], v[68:69] op_sel_hi:[1,0]
	v_pk_mul_f32 v[52:53], v[64:65], v[68:69] op_sel_hi:[1,0]
	global_store_dwordx2 v[66:67], v[34:35], off offset:96
	v_pk_mul_f32 v[34:35], v[46:47], v[68:69] op_sel_hi:[1,0]
	v_pk_mul_f32 v[36:37], v[48:49], v[68:69] op_sel_hi:[1,0]
	global_store_dwordx2 v[66:67], v[18:19], off offset:160
	v_pk_mul_f32 v[18:19], v[30:31], v[68:69] op_sel_hi:[1,0]
	v_pk_mul_f32 v[20:21], v[32:33], v[68:69] op_sel_hi:[1,0]
	global_store_dwordx2 v[66:67], v[2:3], off offset:224
	v_pk_mul_f32 v[2:3], v[14:15], v[68:69] op_sel_hi:[1,0]
	v_pk_mul_f32 v[4:5], v[16:17], v[68:69] op_sel_hi:[1,0]
	v_cvt_pk_bf16_f32 v50, v50, v51
	v_cvt_pk_bf16_f32 v51, v52, v53
	v_cvt_pk_bf16_f32 v34, v34, v35
	v_cvt_pk_bf16_f32 v35, v36, v37
	v_cvt_pk_bf16_f32 v18, v18, v19
	v_cvt_pk_bf16_f32 v19, v20, v21
	v_cvt_pk_bf16_f32 v2, v2, v3
	v_cvt_pk_bf16_f32 v3, v4, v5
	global_store_dwordx2 v[66:67], v[50:51], off offset:48
	global_store_dwordx2 v[66:67], v[34:35], off offset:112
	global_store_dwordx2 v[66:67], v[18:19], off offset:176
	global_store_dwordx2 v[66:67], v[2:3], off offset:240
	s_cbranch_scc0 .LBB0_830
